# P1/P4 k-loops: back edge rotated (section 7.11): the loop-back branch is taken before the barrier, the barrier is the loop head, the exit path has its own barrier copy
# baseline (speedup 1.0000x reference)
.LBB0_145:
	s_add_u32 s27, s50, 0x100
	s_addc_u32 s56, s51, 0
	s_mov_b32 s57, -2
	s_waitcnt lgkmcnt(0)
	ds_read_b128 v[128:131], v188
	ds_read_b128 v[132:135], v188 offset:1024
	ds_read_b128 v[136:139], v188 offset:2048
	ds_read_b128 v[140:143], v188 offset:3072
	ds_read_b128 v[144:147], v189
	ds_read_b128 v[148:151], v189 offset:1024
	ds_read_b128 v[176:179], v189 offset:2048
	ds_read_b128 v[180:183], v189 offset:3072
	s_add_u32 s50, s48, 0x100
	s_addc_u32 s51, s49, 0
	s_cmp_eq_u32 s57, 28
	s_cselect_b32 s55, s21, s51
	s_cselect_b32 s54, s20, s50
	s_cselect_b32 s53, s23, s56
	s_cselect_b32 s52, s22, s27
	v_lshl_add_u64 v[184:185], s[48:49], 0, v[170:171]
	s_add_i32 m0, s60, 0xc000
	ds_read_b128 v[194:197], v190
	ds_read_b128 v[198:201], v190 offset:1024
	ds_read_b128 v[202:205], v190 offset:2048
	ds_read_b128 v[206:209], v190 offset:3072
	ds_read_b128 v[210:213], v190 offset:4096
	ds_read_b128 v[214:217], v190 offset:5120
	ds_read_b128 v[218:221], v190 offset:6144
	ds_read_b128 v[222:225], v190 offset:7168
	global_load_lds_dwordx4 v[184:185], off
	v_lshl_add_u64 v[184:185], s[48:49], 0, v[172:173]
	s_add_i32 m0, s60, 0xe000
	s_nop 0
	global_load_lds_dwordx4 v[184:185], off
	s_waitcnt vmcnt(8) lgkmcnt(0)
	s_setprio 1
	s_barrier
	v_mfma_f32_16x16x32_bf16 v[120:123], v[128:131], v[194:197], 0
	v_mfma_f32_16x16x32_bf16 v[124:127], v[136:139], v[194:197], 0
	v_mfma_f32_16x16x32_bf16 v[108:111], v[128:131], v[202:205], 0
	v_mfma_f32_16x16x32_bf16 v[104:107], v[136:139], v[202:205], 0
	v_mfma_f32_16x16x32_bf16 v[92:95], v[128:131], v[210:213], 0
	v_mfma_f32_16x16x32_bf16 v[88:91], v[136:139], v[210:213], 0
	v_mfma_f32_16x16x32_bf16 v[76:79], v[128:131], v[218:221], 0
	v_mfma_f32_16x16x32_bf16 v[72:75], v[136:139], v[218:221], 0
	v_mfma_f32_16x16x32_bf16 v[120:123], v[132:135], v[198:201], v[120:123]
	v_mfma_f32_16x16x32_bf16 v[124:127], v[140:143], v[198:201], v[124:127]
	v_mfma_f32_16x16x32_bf16 v[108:111], v[132:135], v[206:209], v[108:111]
	v_mfma_f32_16x16x32_bf16 v[104:107], v[140:143], v[206:209], v[104:107]
	v_mfma_f32_16x16x32_bf16 v[92:95], v[132:135], v[214:217], v[92:95]
	v_mfma_f32_16x16x32_bf16 v[88:91], v[140:143], v[214:217], v[88:91]
	v_mfma_f32_16x16x32_bf16 v[76:79], v[132:135], v[222:225], v[76:79]
	v_mfma_f32_16x16x32_bf16 v[72:75], v[140:143], v[222:225], v[72:75]
	s_setprio 0
	s_setprio 1
	v_mfma_f32_16x16x32_bf16 v[112:115], v[144:147], v[194:197], 0
	v_mfma_f32_16x16x32_bf16 v[116:119], v[176:179], v[194:197], 0
	v_mfma_f32_16x16x32_bf16 v[100:103], v[144:147], v[202:205], 0
	v_mfma_f32_16x16x32_bf16 v[96:99], v[176:179], v[202:205], 0
	v_mfma_f32_16x16x32_bf16 v[84:87], v[144:147], v[210:213], 0
	v_mfma_f32_16x16x32_bf16 v[80:83], v[176:179], v[210:213], 0
	v_mfma_f32_16x16x32_bf16 v[68:71], v[144:147], v[218:221], 0
	v_mfma_f32_16x16x32_bf16 v[64:67], v[176:179], v[218:221], 0
	v_mfma_f32_16x16x32_bf16 v[112:115], v[148:151], v[198:201], v[112:115]
	v_mfma_f32_16x16x32_bf16 v[116:119], v[180:183], v[198:201], v[116:119]
	v_mfma_f32_16x16x32_bf16 v[100:103], v[148:151], v[206:209], v[100:103]
	v_mfma_f32_16x16x32_bf16 v[96:99], v[180:183], v[206:209], v[96:99]
	v_mfma_f32_16x16x32_bf16 v[84:87], v[148:151], v[214:217], v[84:87]
	v_mfma_f32_16x16x32_bf16 v[80:83], v[180:183], v[214:217], v[80:83]
	v_mfma_f32_16x16x32_bf16 v[68:71], v[148:151], v[222:225], v[68:71]
	v_mfma_f32_16x16x32_bf16 v[64:67], v[180:183], v[222:225], v[64:67]
	s_barrier
	s_setprio 0
	s_add_i32 s48, s71, s3
	v_lshl_add_u64 v[184:185], s[52:53], 0, v[154:155]
	s_mov_b32 m0, s48
	ds_read_b128 v[194:197], v190 offset:16384
	ds_read_b128 v[198:201], v190 offset:17408
	ds_read_b128 v[202:205], v190 offset:18432
	ds_read_b128 v[206:209], v190 offset:19456
	ds_read_b128 v[210:213], v190 offset:20480
	ds_read_b128 v[214:217], v190 offset:21504
	ds_read_b128 v[218:221], v190 offset:22528
	ds_read_b128 v[222:225], v190 offset:23552
	global_load_lds_dwordx4 v[184:185], off
	s_add_i32 m0, s48, 0x2000
	s_add_u32 s48, s52, 0x80000
	v_lshl_add_u64 v[226:227], s[52:53], 0, v[158:159]
	s_addc_u32 s49, s53, 0
	s_add_i32 s58, s72, s3
	global_load_lds_dwordx4 v[226:227], off
	v_lshl_add_u64 v[228:229], s[48:49], 0, v[154:155]
	s_mov_b32 m0, s58
	v_lshl_add_u64 v[230:231], s[54:55], 0, v[156:157]
	global_load_lds_dwordx4 v[228:229], off
	v_lshl_add_u64 v[228:229], s[48:49], 0, v[158:159]
	s_add_i32 m0, s58, 0x2000
	s_nop 0
	global_load_lds_dwordx4 v[228:229], off
	v_lshl_add_u64 v[228:229], s[54:55], 0, v[152:153]
	s_mov_b32 m0, s60
	s_nop 0
	global_load_lds_dwordx4 v[228:229], off
	s_mov_b32 m0, s61
	s_nop 0
	global_load_lds_dwordx4 v[230:231], off
	s_waitcnt vmcnt(8) lgkmcnt(0)
	s_setprio 1
	s_barrier
	v_mfma_f32_16x16x32_bf16 v[60:63], v[128:131], v[194:197], 0
	v_mfma_f32_16x16x32_bf16 v[56:59], v[136:139], v[194:197], 0
	v_mfma_f32_16x16x32_bf16 v[44:47], v[128:131], v[202:205], 0
	v_mfma_f32_16x16x32_bf16 v[40:43], v[136:139], v[202:205], 0
	v_mfma_f32_16x16x32_bf16 v[28:31], v[128:131], v[210:213], 0
	v_mfma_f32_16x16x32_bf16 v[24:27], v[136:139], v[210:213], 0
	v_mfma_f32_16x16x32_bf16 v[12:15], v[128:131], v[218:221], 0
	v_mfma_f32_16x16x32_bf16 v[8:11], v[136:139], v[218:221], 0
	v_mfma_f32_16x16x32_bf16 v[60:63], v[132:135], v[198:201], v[60:63]
	v_mfma_f32_16x16x32_bf16 v[56:59], v[140:143], v[198:201], v[56:59]
	v_mfma_f32_16x16x32_bf16 v[44:47], v[132:135], v[206:209], v[44:47]
	v_mfma_f32_16x16x32_bf16 v[40:43], v[140:143], v[206:209], v[40:43]
	v_mfma_f32_16x16x32_bf16 v[28:31], v[132:135], v[214:217], v[28:31]
	v_mfma_f32_16x16x32_bf16 v[24:27], v[140:143], v[214:217], v[24:27]
	v_mfma_f32_16x16x32_bf16 v[12:15], v[132:135], v[222:225], v[12:15]
	v_mfma_f32_16x16x32_bf16 v[8:11], v[140:143], v[222:225], v[8:11]
	s_setprio 0
	s_setprio 1
	v_mfma_f32_16x16x32_bf16 v[52:55], v[144:147], v[194:197], 0
	v_mfma_f32_16x16x32_bf16 v[48:51], v[176:179], v[194:197], 0
	v_mfma_f32_16x16x32_bf16 v[36:39], v[144:147], v[202:205], 0
	v_mfma_f32_16x16x32_bf16 v[32:35], v[176:179], v[202:205], 0
	v_mfma_f32_16x16x32_bf16 v[20:23], v[144:147], v[210:213], 0
	v_mfma_f32_16x16x32_bf16 v[16:19], v[176:179], v[210:213], 0
	v_mfma_f32_16x16x32_bf16 v[4:7], v[144:147], v[218:221], 0
	v_mfma_f32_16x16x32_bf16 v[0:3], v[176:179], v[218:221], 0
	v_mfma_f32_16x16x32_bf16 v[52:55], v[148:151], v[198:201], v[52:55]
	v_mfma_f32_16x16x32_bf16 v[48:51], v[180:183], v[198:201], v[48:51]
	v_mfma_f32_16x16x32_bf16 v[36:39], v[148:151], v[206:209], v[36:39]
	v_mfma_f32_16x16x32_bf16 v[32:35], v[180:183], v[206:209], v[32:35]
	v_mfma_f32_16x16x32_bf16 v[20:23], v[148:151], v[214:217], v[20:23]
	v_mfma_f32_16x16x32_bf16 v[16:19], v[180:183], v[214:217], v[16:19]
	v_mfma_f32_16x16x32_bf16 v[4:7], v[148:151], v[222:225], v[4:7]
	v_mfma_f32_16x16x32_bf16 v[0:3], v[180:183], v[222:225], v[0:3]
	s_barrier
	s_setprio 0
	s_branch .Lpeel_mid_p1
	s_nop 0
	s_nop 0
.Lrot_p1:
	s_barrier
	s_setprio 0
.LBB0_146:
	ds_read_b128 v[128:131], v188
	ds_read_b128 v[132:135], v188 offset:1024
	ds_read_b128 v[136:139], v188 offset:2048
	ds_read_b128 v[140:143], v188 offset:3072
	ds_read_b128 v[144:147], v189
	ds_read_b128 v[148:151], v189 offset:1024
	ds_read_b128 v[176:179], v189 offset:2048
	ds_read_b128 v[180:183], v189 offset:3072
	s_add_u32 s50, s48, 0x100
	s_addc_u32 s51, s49, 0
	s_cmp_eq_u32 s57, 28
	s_cselect_b32 s55, s21, s51
	s_cselect_b32 s54, s20, s50
	s_cselect_b32 s53, s23, s56
	s_cselect_b32 s52, s22, s27
	v_lshl_add_u64 v[184:185], s[48:49], 0, v[170:171]
	s_add_i32 m0, s60, 0xc000
	ds_read_b128 v[194:197], v190
	ds_read_b128 v[198:201], v190 offset:1024
	ds_read_b128 v[202:205], v190 offset:2048
	ds_read_b128 v[206:209], v190 offset:3072
	ds_read_b128 v[210:213], v190 offset:4096
	ds_read_b128 v[214:217], v190 offset:5120
	ds_read_b128 v[218:221], v190 offset:6144
	ds_read_b128 v[222:225], v190 offset:7168
	global_load_lds_dwordx4 v[184:185], off
	v_lshl_add_u64 v[184:185], s[48:49], 0, v[172:173]
	s_add_i32 m0, s60, 0xe000
	s_nop 0
	global_load_lds_dwordx4 v[184:185], off
	s_waitcnt vmcnt(8) lgkmcnt(0)
	s_setprio 1
	s_barrier
	v_mfma_f32_16x16x32_bf16 v[120:123], v[128:131], v[194:197], v[120:123]
	v_mfma_f32_16x16x32_bf16 v[124:127], v[136:139], v[194:197], v[124:127]
	v_mfma_f32_16x16x32_bf16 v[108:111], v[128:131], v[202:205], v[108:111]
	v_mfma_f32_16x16x32_bf16 v[104:107], v[136:139], v[202:205], v[104:107]
	v_mfma_f32_16x16x32_bf16 v[92:95], v[128:131], v[210:213], v[92:95]
	v_mfma_f32_16x16x32_bf16 v[88:91], v[136:139], v[210:213], v[88:91]
	v_mfma_f32_16x16x32_bf16 v[76:79], v[128:131], v[218:221], v[76:79]
	v_mfma_f32_16x16x32_bf16 v[72:75], v[136:139], v[218:221], v[72:75]
	v_mfma_f32_16x16x32_bf16 v[120:123], v[132:135], v[198:201], v[120:123]
	v_mfma_f32_16x16x32_bf16 v[124:127], v[140:143], v[198:201], v[124:127]
	v_mfma_f32_16x16x32_bf16 v[108:111], v[132:135], v[206:209], v[108:111]
	v_mfma_f32_16x16x32_bf16 v[104:107], v[140:143], v[206:209], v[104:107]
	v_mfma_f32_16x16x32_bf16 v[92:95], v[132:135], v[214:217], v[92:95]
	v_mfma_f32_16x16x32_bf16 v[88:91], v[140:143], v[214:217], v[88:91]
	v_mfma_f32_16x16x32_bf16 v[76:79], v[132:135], v[222:225], v[76:79]
	v_mfma_f32_16x16x32_bf16 v[72:75], v[140:143], v[222:225], v[72:75]
	s_setprio 0
	s_setprio 1
	v_mfma_f32_16x16x32_bf16 v[112:115], v[144:147], v[194:197], v[112:115]
	v_mfma_f32_16x16x32_bf16 v[116:119], v[176:179], v[194:197], v[116:119]
	v_mfma_f32_16x16x32_bf16 v[100:103], v[144:147], v[202:205], v[100:103]
	v_mfma_f32_16x16x32_bf16 v[96:99], v[176:179], v[202:205], v[96:99]
	v_mfma_f32_16x16x32_bf16 v[84:87], v[144:147], v[210:213], v[84:87]
	v_mfma_f32_16x16x32_bf16 v[80:83], v[176:179], v[210:213], v[80:83]
	v_mfma_f32_16x16x32_bf16 v[68:71], v[144:147], v[218:221], v[68:71]
	v_mfma_f32_16x16x32_bf16 v[64:67], v[176:179], v[218:221], v[64:67]
	v_mfma_f32_16x16x32_bf16 v[112:115], v[148:151], v[198:201], v[112:115]
	v_mfma_f32_16x16x32_bf16 v[116:119], v[180:183], v[198:201], v[116:119]
	v_mfma_f32_16x16x32_bf16 v[100:103], v[148:151], v[206:209], v[100:103]
	v_mfma_f32_16x16x32_bf16 v[96:99], v[180:183], v[206:209], v[96:99]
	v_mfma_f32_16x16x32_bf16 v[84:87], v[148:151], v[214:217], v[84:87]
	v_mfma_f32_16x16x32_bf16 v[80:83], v[180:183], v[214:217], v[80:83]
	v_mfma_f32_16x16x32_bf16 v[68:71], v[148:151], v[222:225], v[68:71]
	v_mfma_f32_16x16x32_bf16 v[64:67], v[180:183], v[222:225], v[64:67]
	s_barrier
	s_setprio 0
	s_add_i32 s48, s71, s3
	v_lshl_add_u64 v[184:185], s[52:53], 0, v[154:155]
	s_mov_b32 m0, s48
	ds_read_b128 v[194:197], v190 offset:16384
	ds_read_b128 v[198:201], v190 offset:17408
	ds_read_b128 v[202:205], v190 offset:18432
	ds_read_b128 v[206:209], v190 offset:19456
	ds_read_b128 v[210:213], v190 offset:20480
	ds_read_b128 v[214:217], v190 offset:21504
	ds_read_b128 v[218:221], v190 offset:22528
	ds_read_b128 v[222:225], v190 offset:23552
	global_load_lds_dwordx4 v[184:185], off
	s_add_i32 m0, s48, 0x2000
	s_add_u32 s48, s52, 0x80000
	v_lshl_add_u64 v[226:227], s[52:53], 0, v[158:159]
	s_addc_u32 s49, s53, 0
	s_add_i32 s58, s72, s3
	global_load_lds_dwordx4 v[226:227], off
	v_lshl_add_u64 v[228:229], s[48:49], 0, v[154:155]
	s_mov_b32 m0, s58
	v_lshl_add_u64 v[230:231], s[54:55], 0, v[156:157]
	global_load_lds_dwordx4 v[228:229], off
	v_lshl_add_u64 v[228:229], s[48:49], 0, v[158:159]
	s_add_i32 m0, s58, 0x2000
	s_nop 0
	global_load_lds_dwordx4 v[228:229], off
	v_lshl_add_u64 v[228:229], s[54:55], 0, v[152:153]
	s_mov_b32 m0, s60
	s_nop 0
	global_load_lds_dwordx4 v[228:229], off
	s_mov_b32 m0, s61
	s_nop 0
	global_load_lds_dwordx4 v[230:231], off
	s_waitcnt vmcnt(8) lgkmcnt(0)
	s_setprio 1
	s_barrier
	v_mfma_f32_16x16x32_bf16 v[60:63], v[128:131], v[194:197], v[60:63]
	v_mfma_f32_16x16x32_bf16 v[56:59], v[136:139], v[194:197], v[56:59]
	v_mfma_f32_16x16x32_bf16 v[44:47], v[128:131], v[202:205], v[44:47]
	v_mfma_f32_16x16x32_bf16 v[40:43], v[136:139], v[202:205], v[40:43]
	v_mfma_f32_16x16x32_bf16 v[28:31], v[128:131], v[210:213], v[28:31]
	v_mfma_f32_16x16x32_bf16 v[24:27], v[136:139], v[210:213], v[24:27]
	v_mfma_f32_16x16x32_bf16 v[12:15], v[128:131], v[218:221], v[12:15]
	v_mfma_f32_16x16x32_bf16 v[8:11], v[136:139], v[218:221], v[8:11]
	v_mfma_f32_16x16x32_bf16 v[60:63], v[132:135], v[198:201], v[60:63]
	v_mfma_f32_16x16x32_bf16 v[56:59], v[140:143], v[198:201], v[56:59]
	v_mfma_f32_16x16x32_bf16 v[44:47], v[132:135], v[206:209], v[44:47]
	v_mfma_f32_16x16x32_bf16 v[40:43], v[140:143], v[206:209], v[40:43]
	v_mfma_f32_16x16x32_bf16 v[28:31], v[132:135], v[214:217], v[28:31]
	v_mfma_f32_16x16x32_bf16 v[24:27], v[140:143], v[214:217], v[24:27]
	v_mfma_f32_16x16x32_bf16 v[12:15], v[132:135], v[222:225], v[12:15]
	v_mfma_f32_16x16x32_bf16 v[8:11], v[140:143], v[222:225], v[8:11]
	s_setprio 0
	s_setprio 1
	v_mfma_f32_16x16x32_bf16 v[52:55], v[144:147], v[194:197], v[52:55]
	v_mfma_f32_16x16x32_bf16 v[48:51], v[176:179], v[194:197], v[48:51]
	v_mfma_f32_16x16x32_bf16 v[36:39], v[144:147], v[202:205], v[36:39]
	v_mfma_f32_16x16x32_bf16 v[32:35], v[176:179], v[202:205], v[32:35]
	v_mfma_f32_16x16x32_bf16 v[20:23], v[144:147], v[210:213], v[20:23]
	v_mfma_f32_16x16x32_bf16 v[16:19], v[176:179], v[210:213], v[16:19]
	v_mfma_f32_16x16x32_bf16 v[4:7], v[144:147], v[218:221], v[4:7]
	v_mfma_f32_16x16x32_bf16 v[0:3], v[176:179], v[218:221], v[0:3]
	v_mfma_f32_16x16x32_bf16 v[52:55], v[148:151], v[198:201], v[52:55]
	v_mfma_f32_16x16x32_bf16 v[48:51], v[180:183], v[198:201], v[48:51]
	v_mfma_f32_16x16x32_bf16 v[36:39], v[148:151], v[206:209], v[36:39]
	v_mfma_f32_16x16x32_bf16 v[32:35], v[180:183], v[206:209], v[32:35]
	v_mfma_f32_16x16x32_bf16 v[20:23], v[148:151], v[214:217], v[20:23]
	v_mfma_f32_16x16x32_bf16 v[16:19], v[180:183], v[214:217], v[16:19]
	v_mfma_f32_16x16x32_bf16 v[4:7], v[148:151], v[222:225], v[4:7]
	v_mfma_f32_16x16x32_bf16 v[0:3], v[180:183], v[222:225], v[0:3]
	s_barrier
	s_setprio 0
.Lpeel_mid_p1:
	s_add_i32 s58, 0, 0x18000
	s_add_i32 s59, 0, 0x1c000
	v_add_u32_e32 v140, s58, v186
	v_add_u32_e32 v160, s59, v186
	ds_read_b128 v[128:131], v140
	ds_read_b128 v[132:135], v140 offset:1024
	ds_read_b128 v[136:139], v140 offset:2048
	ds_read_b128 v[140:143], v140 offset:3072
	ds_read_b128 v[144:147], v160
	ds_read_b128 v[148:151], v160 offset:1024
	ds_read_b128 v[176:179], v160 offset:2048
	ds_read_b128 v[180:183], v160 offset:3072
	s_add_u32 s48, s54, 0xa0000
	s_addc_u32 s49, s55, 0
	s_mov_b32 m0, s62
	v_lshl_add_u64 v[232:233], s[48:49], 0, v[152:153]
	ds_read_b128 v[194:197], v190 offset:32768
	ds_read_b128 v[198:201], v190 offset:33792
	ds_read_b128 v[202:205], v190 offset:34816
	ds_read_b128 v[206:209], v190 offset:35840
	ds_read_b128 v[210:213], v190 offset:36864
	ds_read_b128 v[214:217], v190 offset:37888
	ds_read_b128 v[218:221], v190 offset:38912
	ds_read_b128 v[222:225], v190 offset:39936
	global_load_lds_dwordx4 v[232:233], off
	v_lshl_add_u64 v[232:233], s[48:49], 0, v[156:157]
	s_mov_b32 m0, s63
	s_nop 0
	global_load_lds_dwordx4 v[232:233], off
	s_waitcnt vmcnt(8) lgkmcnt(0)
	s_setprio 1
	s_barrier
	v_mfma_f32_16x16x32_bf16 v[120:123], v[128:131], v[194:197], v[120:123]
	v_mfma_f32_16x16x32_bf16 v[124:127], v[136:139], v[194:197], v[124:127]
	v_mfma_f32_16x16x32_bf16 v[108:111], v[128:131], v[202:205], v[108:111]
	v_mfma_f32_16x16x32_bf16 v[104:107], v[136:139], v[202:205], v[104:107]
	v_mfma_f32_16x16x32_bf16 v[92:95], v[128:131], v[210:213], v[92:95]
	v_mfma_f32_16x16x32_bf16 v[88:91], v[136:139], v[210:213], v[88:91]
	v_mfma_f32_16x16x32_bf16 v[76:79], v[128:131], v[218:221], v[76:79]
	v_mfma_f32_16x16x32_bf16 v[72:75], v[136:139], v[218:221], v[72:75]
	v_mfma_f32_16x16x32_bf16 v[120:123], v[132:135], v[198:201], v[120:123]
	v_mfma_f32_16x16x32_bf16 v[124:127], v[140:143], v[198:201], v[124:127]
	v_mfma_f32_16x16x32_bf16 v[108:111], v[132:135], v[206:209], v[108:111]
	v_mfma_f32_16x16x32_bf16 v[104:107], v[140:143], v[206:209], v[104:107]
	v_mfma_f32_16x16x32_bf16 v[92:95], v[132:135], v[214:217], v[92:95]
	v_mfma_f32_16x16x32_bf16 v[88:91], v[140:143], v[214:217], v[88:91]
	v_mfma_f32_16x16x32_bf16 v[76:79], v[132:135], v[222:225], v[76:79]
	v_mfma_f32_16x16x32_bf16 v[72:75], v[140:143], v[222:225], v[72:75]
	s_setprio 0
	s_setprio 1
	v_mfma_f32_16x16x32_bf16 v[112:115], v[144:147], v[194:197], v[112:115]
	v_mfma_f32_16x16x32_bf16 v[116:119], v[176:179], v[194:197], v[116:119]
	v_mfma_f32_16x16x32_bf16 v[100:103], v[144:147], v[202:205], v[100:103]
	v_mfma_f32_16x16x32_bf16 v[96:99], v[176:179], v[202:205], v[96:99]
	v_mfma_f32_16x16x32_bf16 v[84:87], v[144:147], v[210:213], v[84:87]
	v_mfma_f32_16x16x32_bf16 v[80:83], v[176:179], v[210:213], v[80:83]
	v_mfma_f32_16x16x32_bf16 v[68:71], v[144:147], v[218:221], v[68:71]
	v_mfma_f32_16x16x32_bf16 v[64:67], v[176:179], v[218:221], v[64:67]
	v_mfma_f32_16x16x32_bf16 v[112:115], v[148:151], v[198:201], v[112:115]
	v_mfma_f32_16x16x32_bf16 v[116:119], v[180:183], v[198:201], v[116:119]
	v_mfma_f32_16x16x32_bf16 v[100:103], v[148:151], v[206:209], v[100:103]
	v_mfma_f32_16x16x32_bf16 v[96:99], v[180:183], v[206:209], v[96:99]
	v_mfma_f32_16x16x32_bf16 v[84:87], v[148:151], v[214:217], v[84:87]
	v_mfma_f32_16x16x32_bf16 v[80:83], v[180:183], v[214:217], v[80:83]
	v_mfma_f32_16x16x32_bf16 v[68:71], v[148:151], v[222:225], v[68:71]
	v_mfma_f32_16x16x32_bf16 v[64:67], v[180:183], v[222:225], v[64:67]
	s_barrier
	s_setprio 0
	s_add_i32 s48, s58, s3
	v_lshl_add_u64 v[184:185], v[184:185], 0, s[14:15]
	s_mov_b32 m0, s48
	ds_read_b128 v[194:197], v190 offset:49152
	ds_read_b128 v[198:201], v190 offset:50176
	ds_read_b128 v[202:205], v190 offset:51200
	ds_read_b128 v[206:209], v190 offset:52224
	ds_read_b128 v[210:213], v190 offset:53248
	ds_read_b128 v[214:217], v190 offset:54272
	ds_read_b128 v[218:221], v190 offset:55296
	ds_read_b128 v[222:225], v190 offset:56320
	global_load_lds_dwordx4 v[184:185], off
	s_add_i32 m0, s48, 0x2000
	s_add_u32 s48, s52, 0x80080
	v_lshl_add_u64 v[184:185], v[226:227], 0, s[14:15]
	s_addc_u32 s49, s53, 0
	s_add_i32 s52, s59, s3
	global_load_lds_dwordx4 v[184:185], off
	v_lshl_add_u64 v[184:185], s[48:49], 0, v[154:155]
	s_mov_b32 m0, s52
	s_nop 0
	global_load_lds_dwordx4 v[184:185], off
	v_lshl_add_u64 v[184:185], s[48:49], 0, v[158:159]
	s_add_i32 m0, s52, 0x2000
	s_nop 0
	global_load_lds_dwordx4 v[184:185], off
	v_lshl_add_u64 v[184:185], v[228:229], 0, s[14:15]
	s_mov_b32 m0, s66
	s_nop 0
	global_load_lds_dwordx4 v[184:185], off
	v_lshl_add_u64 v[184:185], v[230:231], 0, s[14:15]
	s_mov_b32 m0, s67
	s_nop 0
	global_load_lds_dwordx4 v[184:185], off
	s_waitcnt vmcnt(8) lgkmcnt(0)
	s_setprio 1
	s_barrier
	v_mfma_f32_16x16x32_bf16 v[60:63], v[128:131], v[194:197], v[60:63]
	v_mfma_f32_16x16x32_bf16 v[56:59], v[136:139], v[194:197], v[56:59]
	v_mfma_f32_16x16x32_bf16 v[44:47], v[128:131], v[202:205], v[44:47]
	v_mfma_f32_16x16x32_bf16 v[40:43], v[136:139], v[202:205], v[40:43]
	v_mfma_f32_16x16x32_bf16 v[28:31], v[128:131], v[210:213], v[28:31]
	v_mfma_f32_16x16x32_bf16 v[24:27], v[136:139], v[210:213], v[24:27]
	v_mfma_f32_16x16x32_bf16 v[12:15], v[128:131], v[218:221], v[12:15]
	v_mfma_f32_16x16x32_bf16 v[8:11], v[136:139], v[218:221], v[8:11]
	v_mfma_f32_16x16x32_bf16 v[60:63], v[132:135], v[198:201], v[60:63]
	v_mfma_f32_16x16x32_bf16 v[56:59], v[140:143], v[198:201], v[56:59]
	v_mfma_f32_16x16x32_bf16 v[44:47], v[132:135], v[206:209], v[44:47]
	v_mfma_f32_16x16x32_bf16 v[40:43], v[140:143], v[206:209], v[40:43]
	v_mfma_f32_16x16x32_bf16 v[28:31], v[132:135], v[214:217], v[28:31]
	v_mfma_f32_16x16x32_bf16 v[24:27], v[140:143], v[214:217], v[24:27]
	v_mfma_f32_16x16x32_bf16 v[12:15], v[132:135], v[222:225], v[12:15]
	v_mfma_f32_16x16x32_bf16 v[8:11], v[140:143], v[222:225], v[8:11]
	s_setprio 0
	s_setprio 1
	v_mfma_f32_16x16x32_bf16 v[52:55], v[144:147], v[194:197], v[52:55]
	v_mfma_f32_16x16x32_bf16 v[48:51], v[176:179], v[194:197], v[48:51]
	v_mfma_f32_16x16x32_bf16 v[36:39], v[144:147], v[202:205], v[36:39]
	v_mfma_f32_16x16x32_bf16 v[32:35], v[176:179], v[202:205], v[32:35]
	s_add_i32 s57, s57, 2
	v_mfma_f32_16x16x32_bf16 v[20:23], v[144:147], v[210:213], v[20:23]
	s_add_u32 s27, s27, 0x100
	v_mfma_f32_16x16x32_bf16 v[16:19], v[176:179], v[210:213], v[16:19]
	s_addc_u32 s56, s56, 0
	v_mfma_f32_16x16x32_bf16 v[4:7], v[144:147], v[218:221], v[4:7]
	s_cmp_gt_u32 s57, 29
	v_mfma_f32_16x16x32_bf16 v[0:3], v[176:179], v[218:221], v[0:3]
	s_mov_b64 s[48:49], s[50:51]
	v_mfma_f32_16x16x32_bf16 v[52:55], v[148:151], v[198:201], v[52:55]
	v_mfma_f32_16x16x32_bf16 v[48:51], v[180:183], v[198:201], v[48:51]
	v_mfma_f32_16x16x32_bf16 v[36:39], v[148:151], v[206:209], v[36:39]
	v_mfma_f32_16x16x32_bf16 v[32:35], v[180:183], v[206:209], v[32:35]
	v_mfma_f32_16x16x32_bf16 v[20:23], v[148:151], v[214:217], v[20:23]
	v_mfma_f32_16x16x32_bf16 v[16:19], v[180:183], v[214:217], v[16:19]
	v_mfma_f32_16x16x32_bf16 v[4:7], v[148:151], v[222:225], v[4:7]
	v_mfma_f32_16x16x32_bf16 v[0:3], v[180:183], v[222:225], v[0:3]
	s_cbranch_scc0 .Lrot_p1
	s_barrier
	s_setprio 0
	s_and_b64 vcc, exec, s[18:19]
	s_cbranch_vccz .LBB0_149
	s_barrier

.LBB0_671:
	s_add_u32 s6, s6, 0x80080
	s_addc_u32 s7, s7, 0
	s_add_u32 s5, s40, 0x100
	s_addc_u32 s25, s41, 0
	s_mov_b32 s56, -2
	ds_read_b128 v[128:131], v185
	ds_read_b128 v[132:135], v185 offset:1024
	ds_read_b128 v[136:139], v185 offset:2048
	ds_read_b128 v[140:143], v185 offset:3072
	ds_read_b128 v[162:165], v186
	ds_read_b128 v[166:169], v186 offset:1024
	ds_read_b128 v[170:173], v186 offset:2048
	ds_read_b128 v[174:177], v186 offset:3072
	s_add_u32 s38, s6, 0xfff80080
	s_addc_u32 s39, s7, -1
	s_cmp_eq_u32 s56, 28
	s_cselect_b32 s41, s27, s39
	s_cselect_b32 s40, s26, s38
	s_cselect_b32 s39, s23, s25
	s_cselect_b32 s38, s22, s5
	v_lshl_add_u64 v[182:183], s[6:7], 0, v[158:159]
	s_add_i32 m0, s42, 0xc000
	ds_read_b128 v[178:181], v188
	ds_read_b128 v[192:195], v188 offset:1024
	ds_read_b128 v[196:199], v188 offset:2048
	ds_read_b128 v[200:203], v188 offset:3072
	ds_read_b128 v[204:207], v188 offset:4096
	ds_read_b128 v[208:211], v188 offset:5120
	ds_read_b128 v[212:215], v188 offset:6144
	ds_read_b128 v[216:219], v188 offset:7168
	global_load_lds_dwordx4 v[182:183], off
	v_lshl_add_u64 v[182:183], s[6:7], 0, v[160:161]
	s_add_i32 m0, s42, 0xe000
	s_nop 0
	global_load_lds_dwordx4 v[182:183], off
	s_waitcnt vmcnt(8) lgkmcnt(0)
	s_setprio 1
	s_barrier
	v_mfma_f32_16x16x32_bf16 v[124:127], v[128:131], v[178:181], 0
	v_mfma_f32_16x16x32_bf16 v[120:123], v[136:139], v[178:181], 0
	v_mfma_f32_16x16x32_bf16 v[108:111], v[128:131], v[196:199], 0
	v_mfma_f32_16x16x32_bf16 v[104:107], v[136:139], v[196:199], 0
	v_mfma_f32_16x16x32_bf16 v[92:95], v[128:131], v[204:207], 0
	v_mfma_f32_16x16x32_bf16 v[88:91], v[136:139], v[204:207], 0
	v_mfma_f32_16x16x32_bf16 v[76:79], v[128:131], v[212:215], 0
	v_mfma_f32_16x16x32_bf16 v[72:75], v[136:139], v[212:215], 0
	v_mfma_f32_16x16x32_bf16 v[124:127], v[132:135], v[192:195], v[124:127]
	v_mfma_f32_16x16x32_bf16 v[120:123], v[140:143], v[192:195], v[120:123]
	v_mfma_f32_16x16x32_bf16 v[108:111], v[132:135], v[200:203], v[108:111]
	v_mfma_f32_16x16x32_bf16 v[104:107], v[140:143], v[200:203], v[104:107]
	v_mfma_f32_16x16x32_bf16 v[92:95], v[132:135], v[208:211], v[92:95]
	v_mfma_f32_16x16x32_bf16 v[88:91], v[140:143], v[208:211], v[88:91]
	v_mfma_f32_16x16x32_bf16 v[76:79], v[132:135], v[216:219], v[76:79]
	v_mfma_f32_16x16x32_bf16 v[72:75], v[140:143], v[216:219], v[72:75]
	s_setprio 0
	s_setprio 1
	v_mfma_f32_16x16x32_bf16 v[116:119], v[162:165], v[178:181], 0
	v_mfma_f32_16x16x32_bf16 v[112:115], v[170:173], v[178:181], 0
	v_mfma_f32_16x16x32_bf16 v[100:103], v[162:165], v[196:199], 0
	v_mfma_f32_16x16x32_bf16 v[96:99], v[170:173], v[196:199], 0
	v_mfma_f32_16x16x32_bf16 v[84:87], v[162:165], v[204:207], 0
	v_mfma_f32_16x16x32_bf16 v[80:83], v[170:173], v[204:207], 0
	v_mfma_f32_16x16x32_bf16 v[68:71], v[162:165], v[212:215], 0
	v_mfma_f32_16x16x32_bf16 v[64:67], v[170:173], v[212:215], 0
	v_mfma_f32_16x16x32_bf16 v[116:119], v[166:169], v[192:195], v[116:119]
	v_mfma_f32_16x16x32_bf16 v[112:115], v[174:177], v[192:195], v[112:115]
	v_mfma_f32_16x16x32_bf16 v[100:103], v[166:169], v[200:203], v[100:103]
	v_mfma_f32_16x16x32_bf16 v[96:99], v[174:177], v[200:203], v[96:99]
	v_mfma_f32_16x16x32_bf16 v[84:87], v[166:169], v[208:211], v[84:87]
	v_mfma_f32_16x16x32_bf16 v[80:83], v[174:177], v[208:211], v[80:83]
	v_mfma_f32_16x16x32_bf16 v[68:71], v[166:169], v[216:219], v[68:71]
	v_mfma_f32_16x16x32_bf16 v[64:67], v[174:177], v[216:219], v[64:67]
	s_barrier
	s_setprio 0
	s_add_i32 s57, s51, s35
	v_lshl_add_u64 v[182:183], s[38:39], 0, v[148:149]
	s_mov_b32 m0, s57
	ds_read_b128 v[178:181], v188 offset:16384
	ds_read_b128 v[192:195], v188 offset:17408
	ds_read_b128 v[196:199], v188 offset:18432
	ds_read_b128 v[200:203], v188 offset:19456
	ds_read_b128 v[204:207], v188 offset:20480
	ds_read_b128 v[208:211], v188 offset:21504
	ds_read_b128 v[212:215], v188 offset:22528
	ds_read_b128 v[216:219], v188 offset:23552
	global_load_lds_dwordx4 v[182:183], off
	s_add_i32 m0, s57, 0x2000
	s_add_u32 s58, s38, 0x80000
	v_lshl_add_u64 v[220:221], s[38:39], 0, v[144:145]
	s_addc_u32 s59, s39, 0
	s_add_i32 s57, s52, s35
	global_load_lds_dwordx4 v[220:221], off
	v_lshl_add_u64 v[222:223], s[58:59], 0, v[148:149]
	s_mov_b32 m0, s57
	v_lshl_add_u64 v[224:225], s[40:41], 0, v[146:147]
	global_load_lds_dwordx4 v[222:223], off
	v_lshl_add_u64 v[222:223], s[58:59], 0, v[144:145]
	s_add_i32 m0, s57, 0x2000
	s_nop 0
	global_load_lds_dwordx4 v[222:223], off
	v_lshl_add_u64 v[222:223], s[40:41], 0, v[150:151]
	s_mov_b32 m0, s42
	s_nop 0
	global_load_lds_dwordx4 v[222:223], off
	s_mov_b32 m0, s43
	s_nop 0
	global_load_lds_dwordx4 v[224:225], off
	s_waitcnt vmcnt(8) lgkmcnt(0)
	s_setprio 1
	s_barrier
	v_mfma_f32_16x16x32_bf16 v[60:63], v[128:131], v[178:181], 0
	v_mfma_f32_16x16x32_bf16 v[56:59], v[136:139], v[178:181], 0
	v_mfma_f32_16x16x32_bf16 v[44:47], v[128:131], v[196:199], 0
	v_mfma_f32_16x16x32_bf16 v[40:43], v[136:139], v[196:199], 0
	v_mfma_f32_16x16x32_bf16 v[28:31], v[128:131], v[204:207], 0
	v_mfma_f32_16x16x32_bf16 v[24:27], v[136:139], v[204:207], 0
	v_mfma_f32_16x16x32_bf16 v[12:15], v[128:131], v[212:215], 0
	v_mfma_f32_16x16x32_bf16 v[8:11], v[136:139], v[212:215], 0
	v_mfma_f32_16x16x32_bf16 v[60:63], v[132:135], v[192:195], v[60:63]
	v_mfma_f32_16x16x32_bf16 v[56:59], v[140:143], v[192:195], v[56:59]
	v_mfma_f32_16x16x32_bf16 v[44:47], v[132:135], v[200:203], v[44:47]
	v_mfma_f32_16x16x32_bf16 v[40:43], v[140:143], v[200:203], v[40:43]
	v_mfma_f32_16x16x32_bf16 v[28:31], v[132:135], v[208:211], v[28:31]
	v_mfma_f32_16x16x32_bf16 v[24:27], v[140:143], v[208:211], v[24:27]
	v_mfma_f32_16x16x32_bf16 v[12:15], v[132:135], v[216:219], v[12:15]
	v_mfma_f32_16x16x32_bf16 v[8:11], v[140:143], v[216:219], v[8:11]
	s_setprio 0
	s_setprio 1
	v_mfma_f32_16x16x32_bf16 v[52:55], v[162:165], v[178:181], 0
	v_mfma_f32_16x16x32_bf16 v[48:51], v[170:173], v[178:181], 0
	v_mfma_f32_16x16x32_bf16 v[36:39], v[162:165], v[196:199], 0
	v_mfma_f32_16x16x32_bf16 v[32:35], v[170:173], v[196:199], 0
	v_mfma_f32_16x16x32_bf16 v[20:23], v[162:165], v[204:207], 0
	v_mfma_f32_16x16x32_bf16 v[16:19], v[170:173], v[204:207], 0
	v_mfma_f32_16x16x32_bf16 v[4:7], v[162:165], v[212:215], 0
	v_mfma_f32_16x16x32_bf16 v[0:3], v[170:173], v[212:215], 0
	v_mfma_f32_16x16x32_bf16 v[52:55], v[166:169], v[192:195], v[52:55]
	v_mfma_f32_16x16x32_bf16 v[48:51], v[174:177], v[192:195], v[48:51]
	v_mfma_f32_16x16x32_bf16 v[36:39], v[166:169], v[200:203], v[36:39]
	v_mfma_f32_16x16x32_bf16 v[32:35], v[174:177], v[200:203], v[32:35]
	v_mfma_f32_16x16x32_bf16 v[20:23], v[166:169], v[208:211], v[20:23]
	v_mfma_f32_16x16x32_bf16 v[16:19], v[174:177], v[208:211], v[16:19]
	v_mfma_f32_16x16x32_bf16 v[4:7], v[166:169], v[216:219], v[4:7]
	v_mfma_f32_16x16x32_bf16 v[0:3], v[174:177], v[216:219], v[0:3]
	s_barrier
	s_setprio 0
	s_branch .Lpeel_mid_p4
.Lrot_p4:
	s_barrier
	s_setprio 0
.LBB0_672:
	ds_read_b128 v[128:131], v185
	ds_read_b128 v[132:135], v185 offset:1024
	ds_read_b128 v[136:139], v185 offset:2048
	ds_read_b128 v[140:143], v185 offset:3072
	ds_read_b128 v[162:165], v186
	ds_read_b128 v[166:169], v186 offset:1024
	ds_read_b128 v[170:173], v186 offset:2048
	ds_read_b128 v[174:177], v186 offset:3072
	s_add_u32 s38, s6, 0xfff80080
	s_addc_u32 s39, s7, -1
	s_cmp_eq_u32 s56, 28
	s_cselect_b32 s41, s27, s39
	s_cselect_b32 s40, s26, s38
	s_cselect_b32 s39, s23, s25
	s_cselect_b32 s38, s22, s5
	v_lshl_add_u64 v[182:183], s[6:7], 0, v[158:159]
	s_add_i32 m0, s42, 0xc000
	ds_read_b128 v[178:181], v188
	ds_read_b128 v[192:195], v188 offset:1024
	ds_read_b128 v[196:199], v188 offset:2048
	ds_read_b128 v[200:203], v188 offset:3072
	ds_read_b128 v[204:207], v188 offset:4096
	ds_read_b128 v[208:211], v188 offset:5120
	ds_read_b128 v[212:215], v188 offset:6144
	ds_read_b128 v[216:219], v188 offset:7168
	global_load_lds_dwordx4 v[182:183], off
	v_lshl_add_u64 v[182:183], s[6:7], 0, v[160:161]
	s_add_i32 m0, s42, 0xe000
	s_nop 0
	global_load_lds_dwordx4 v[182:183], off
	s_waitcnt vmcnt(8) lgkmcnt(0)
	s_setprio 1
	s_barrier
	v_mfma_f32_16x16x32_bf16 v[124:127], v[128:131], v[178:181], v[124:127]
	v_mfma_f32_16x16x32_bf16 v[120:123], v[136:139], v[178:181], v[120:123]
	v_mfma_f32_16x16x32_bf16 v[108:111], v[128:131], v[196:199], v[108:111]
	v_mfma_f32_16x16x32_bf16 v[104:107], v[136:139], v[196:199], v[104:107]
	v_mfma_f32_16x16x32_bf16 v[92:95], v[128:131], v[204:207], v[92:95]
	v_mfma_f32_16x16x32_bf16 v[88:91], v[136:139], v[204:207], v[88:91]
	v_mfma_f32_16x16x32_bf16 v[76:79], v[128:131], v[212:215], v[76:79]
	v_mfma_f32_16x16x32_bf16 v[72:75], v[136:139], v[212:215], v[72:75]
	v_mfma_f32_16x16x32_bf16 v[124:127], v[132:135], v[192:195], v[124:127]
	v_mfma_f32_16x16x32_bf16 v[120:123], v[140:143], v[192:195], v[120:123]
	v_mfma_f32_16x16x32_bf16 v[108:111], v[132:135], v[200:203], v[108:111]
	v_mfma_f32_16x16x32_bf16 v[104:107], v[140:143], v[200:203], v[104:107]
	v_mfma_f32_16x16x32_bf16 v[92:95], v[132:135], v[208:211], v[92:95]
	v_mfma_f32_16x16x32_bf16 v[88:91], v[140:143], v[208:211], v[88:91]
	v_mfma_f32_16x16x32_bf16 v[76:79], v[132:135], v[216:219], v[76:79]
	v_mfma_f32_16x16x32_bf16 v[72:75], v[140:143], v[216:219], v[72:75]
	s_setprio 0
	s_setprio 1
	v_mfma_f32_16x16x32_bf16 v[116:119], v[162:165], v[178:181], v[116:119]
	v_mfma_f32_16x16x32_bf16 v[112:115], v[170:173], v[178:181], v[112:115]
	v_mfma_f32_16x16x32_bf16 v[100:103], v[162:165], v[196:199], v[100:103]
	v_mfma_f32_16x16x32_bf16 v[96:99], v[170:173], v[196:199], v[96:99]
	v_mfma_f32_16x16x32_bf16 v[84:87], v[162:165], v[204:207], v[84:87]
	v_mfma_f32_16x16x32_bf16 v[80:83], v[170:173], v[204:207], v[80:83]
	v_mfma_f32_16x16x32_bf16 v[68:71], v[162:165], v[212:215], v[68:71]
	v_mfma_f32_16x16x32_bf16 v[64:67], v[170:173], v[212:215], v[64:67]
	v_mfma_f32_16x16x32_bf16 v[116:119], v[166:169], v[192:195], v[116:119]
	v_mfma_f32_16x16x32_bf16 v[112:115], v[174:177], v[192:195], v[112:115]
	v_mfma_f32_16x16x32_bf16 v[100:103], v[166:169], v[200:203], v[100:103]
	v_mfma_f32_16x16x32_bf16 v[96:99], v[174:177], v[200:203], v[96:99]
	v_mfma_f32_16x16x32_bf16 v[84:87], v[166:169], v[208:211], v[84:87]
	v_mfma_f32_16x16x32_bf16 v[80:83], v[174:177], v[208:211], v[80:83]
	v_mfma_f32_16x16x32_bf16 v[68:71], v[166:169], v[216:219], v[68:71]
	v_mfma_f32_16x16x32_bf16 v[64:67], v[174:177], v[216:219], v[64:67]
	s_barrier
	s_setprio 0
	s_add_i32 s57, s51, s35
	v_lshl_add_u64 v[182:183], s[38:39], 0, v[148:149]
	s_mov_b32 m0, s57
	ds_read_b128 v[178:181], v188 offset:16384
	ds_read_b128 v[192:195], v188 offset:17408
	ds_read_b128 v[196:199], v188 offset:18432
	ds_read_b128 v[200:203], v188 offset:19456
	ds_read_b128 v[204:207], v188 offset:20480
	ds_read_b128 v[208:211], v188 offset:21504
	ds_read_b128 v[212:215], v188 offset:22528
	ds_read_b128 v[216:219], v188 offset:23552
	global_load_lds_dwordx4 v[182:183], off
	s_add_i32 m0, s57, 0x2000
	s_add_u32 s58, s38, 0x80000
	v_lshl_add_u64 v[220:221], s[38:39], 0, v[144:145]
	s_addc_u32 s59, s39, 0
	s_add_i32 s57, s52, s35
	global_load_lds_dwordx4 v[220:221], off
	v_lshl_add_u64 v[222:223], s[58:59], 0, v[148:149]
	s_mov_b32 m0, s57
	v_lshl_add_u64 v[224:225], s[40:41], 0, v[146:147]
	global_load_lds_dwordx4 v[222:223], off
	v_lshl_add_u64 v[222:223], s[58:59], 0, v[144:145]
	s_add_i32 m0, s57, 0x2000
	s_nop 0
	global_load_lds_dwordx4 v[222:223], off
	v_lshl_add_u64 v[222:223], s[40:41], 0, v[150:151]
	s_mov_b32 m0, s42
	s_nop 0
	global_load_lds_dwordx4 v[222:223], off
	s_mov_b32 m0, s43
	s_nop 0
	global_load_lds_dwordx4 v[224:225], off
	s_waitcnt vmcnt(8) lgkmcnt(0)
	s_setprio 1
	s_barrier
	v_mfma_f32_16x16x32_bf16 v[60:63], v[128:131], v[178:181], v[60:63]
	v_mfma_f32_16x16x32_bf16 v[56:59], v[136:139], v[178:181], v[56:59]
	v_mfma_f32_16x16x32_bf16 v[44:47], v[128:131], v[196:199], v[44:47]
	v_mfma_f32_16x16x32_bf16 v[40:43], v[136:139], v[196:199], v[40:43]
	v_mfma_f32_16x16x32_bf16 v[28:31], v[128:131], v[204:207], v[28:31]
	v_mfma_f32_16x16x32_bf16 v[24:27], v[136:139], v[204:207], v[24:27]
	v_mfma_f32_16x16x32_bf16 v[12:15], v[128:131], v[212:215], v[12:15]
	v_mfma_f32_16x16x32_bf16 v[8:11], v[136:139], v[212:215], v[8:11]
	v_mfma_f32_16x16x32_bf16 v[60:63], v[132:135], v[192:195], v[60:63]
	v_mfma_f32_16x16x32_bf16 v[56:59], v[140:143], v[192:195], v[56:59]
	v_mfma_f32_16x16x32_bf16 v[44:47], v[132:135], v[200:203], v[44:47]
	v_mfma_f32_16x16x32_bf16 v[40:43], v[140:143], v[200:203], v[40:43]
	v_mfma_f32_16x16x32_bf16 v[28:31], v[132:135], v[208:211], v[28:31]
	v_mfma_f32_16x16x32_bf16 v[24:27], v[140:143], v[208:211], v[24:27]
	v_mfma_f32_16x16x32_bf16 v[12:15], v[132:135], v[216:219], v[12:15]
	v_mfma_f32_16x16x32_bf16 v[8:11], v[140:143], v[216:219], v[8:11]
	s_setprio 0
	s_setprio 1
	v_mfma_f32_16x16x32_bf16 v[52:55], v[162:165], v[178:181], v[52:55]
	v_mfma_f32_16x16x32_bf16 v[48:51], v[170:173], v[178:181], v[48:51]
	v_mfma_f32_16x16x32_bf16 v[36:39], v[162:165], v[196:199], v[36:39]
	v_mfma_f32_16x16x32_bf16 v[32:35], v[170:173], v[196:199], v[32:35]
	v_mfma_f32_16x16x32_bf16 v[20:23], v[162:165], v[204:207], v[20:23]
	v_mfma_f32_16x16x32_bf16 v[16:19], v[170:173], v[204:207], v[16:19]
	v_mfma_f32_16x16x32_bf16 v[4:7], v[162:165], v[212:215], v[4:7]
	v_mfma_f32_16x16x32_bf16 v[0:3], v[170:173], v[212:215], v[0:3]
	v_mfma_f32_16x16x32_bf16 v[52:55], v[166:169], v[192:195], v[52:55]
	v_mfma_f32_16x16x32_bf16 v[48:51], v[174:177], v[192:195], v[48:51]
	v_mfma_f32_16x16x32_bf16 v[36:39], v[166:169], v[200:203], v[36:39]
	v_mfma_f32_16x16x32_bf16 v[32:35], v[174:177], v[200:203], v[32:35]
	v_mfma_f32_16x16x32_bf16 v[20:23], v[166:169], v[208:211], v[20:23]
	v_mfma_f32_16x16x32_bf16 v[16:19], v[174:177], v[208:211], v[16:19]
	v_mfma_f32_16x16x32_bf16 v[4:7], v[166:169], v[216:219], v[4:7]
	v_mfma_f32_16x16x32_bf16 v[0:3], v[174:177], v[216:219], v[0:3]
	s_barrier
	s_setprio 0
.Lpeel_mid_p4:
	s_add_i32 s57, 0, 0x18000
	s_add_i32 s58, 0, 0x1c000
	v_add_u32_e32 v140, s57, v184
	v_add_u32_e32 v174, s58, v184
	ds_read_b128 v[128:131], v140
	ds_read_b128 v[132:135], v140 offset:1024
	ds_read_b128 v[136:139], v140 offset:2048
	ds_read_b128 v[140:143], v140 offset:3072
	ds_read_b128 v[162:165], v174
	ds_read_b128 v[166:169], v174 offset:1024
	ds_read_b128 v[170:173], v174 offset:2048
	ds_read_b128 v[174:177], v174 offset:3072
	s_add_u32 s40, s40, 0x80000
	s_addc_u32 s41, s41, 0
	s_mov_b32 m0, s44
	v_lshl_add_u64 v[226:227], s[40:41], 0, v[150:151]
	ds_read_b128 v[178:181], v188 offset:32768
	ds_read_b128 v[192:195], v188 offset:33792
	ds_read_b128 v[196:199], v188 offset:34816
	ds_read_b128 v[200:203], v188 offset:35840
	ds_read_b128 v[204:207], v188 offset:36864
	ds_read_b128 v[208:211], v188 offset:37888
	ds_read_b128 v[212:215], v188 offset:38912
	ds_read_b128 v[216:219], v188 offset:39936
	global_load_lds_dwordx4 v[226:227], off
	v_lshl_add_u64 v[226:227], s[40:41], 0, v[146:147]
	s_mov_b32 m0, s45
	s_nop 0
	global_load_lds_dwordx4 v[226:227], off
	s_waitcnt vmcnt(8) lgkmcnt(0)
	s_setprio 1
	s_barrier
	v_mfma_f32_16x16x32_bf16 v[124:127], v[128:131], v[178:181], v[124:127]
	v_mfma_f32_16x16x32_bf16 v[120:123], v[136:139], v[178:181], v[120:123]
	v_mfma_f32_16x16x32_bf16 v[108:111], v[128:131], v[196:199], v[108:111]
	v_mfma_f32_16x16x32_bf16 v[104:107], v[136:139], v[196:199], v[104:107]
	v_mfma_f32_16x16x32_bf16 v[92:95], v[128:131], v[204:207], v[92:95]
	v_mfma_f32_16x16x32_bf16 v[88:91], v[136:139], v[204:207], v[88:91]
	v_mfma_f32_16x16x32_bf16 v[76:79], v[128:131], v[212:215], v[76:79]
	v_mfma_f32_16x16x32_bf16 v[72:75], v[136:139], v[212:215], v[72:75]
	v_mfma_f32_16x16x32_bf16 v[124:127], v[132:135], v[192:195], v[124:127]
	v_mfma_f32_16x16x32_bf16 v[120:123], v[140:143], v[192:195], v[120:123]
	v_mfma_f32_16x16x32_bf16 v[108:111], v[132:135], v[200:203], v[108:111]
	v_mfma_f32_16x16x32_bf16 v[104:107], v[140:143], v[200:203], v[104:107]
	v_mfma_f32_16x16x32_bf16 v[92:95], v[132:135], v[208:211], v[92:95]
	v_mfma_f32_16x16x32_bf16 v[88:91], v[140:143], v[208:211], v[88:91]
	v_mfma_f32_16x16x32_bf16 v[76:79], v[132:135], v[216:219], v[76:79]
	v_mfma_f32_16x16x32_bf16 v[72:75], v[140:143], v[216:219], v[72:75]
	s_setprio 0
	s_setprio 1
	v_mfma_f32_16x16x32_bf16 v[116:119], v[162:165], v[178:181], v[116:119]
	v_mfma_f32_16x16x32_bf16 v[112:115], v[170:173], v[178:181], v[112:115]
	v_mfma_f32_16x16x32_bf16 v[100:103], v[162:165], v[196:199], v[100:103]
	v_mfma_f32_16x16x32_bf16 v[96:99], v[170:173], v[196:199], v[96:99]
	v_mfma_f32_16x16x32_bf16 v[84:87], v[162:165], v[204:207], v[84:87]
	v_mfma_f32_16x16x32_bf16 v[80:83], v[170:173], v[204:207], v[80:83]
	v_mfma_f32_16x16x32_bf16 v[68:71], v[162:165], v[212:215], v[68:71]
	v_mfma_f32_16x16x32_bf16 v[64:67], v[170:173], v[212:215], v[64:67]
	v_mfma_f32_16x16x32_bf16 v[116:119], v[166:169], v[192:195], v[116:119]
	v_mfma_f32_16x16x32_bf16 v[112:115], v[174:177], v[192:195], v[112:115]
	v_mfma_f32_16x16x32_bf16 v[100:103], v[166:169], v[200:203], v[100:103]
	v_mfma_f32_16x16x32_bf16 v[96:99], v[174:177], v[200:203], v[96:99]
	v_mfma_f32_16x16x32_bf16 v[84:87], v[166:169], v[208:211], v[84:87]
	v_mfma_f32_16x16x32_bf16 v[80:83], v[174:177], v[208:211], v[80:83]
	v_mfma_f32_16x16x32_bf16 v[68:71], v[166:169], v[216:219], v[68:71]
	v_mfma_f32_16x16x32_bf16 v[64:67], v[174:177], v[216:219], v[64:67]
	s_barrier
	s_setprio 0
	s_add_i32 s40, s57, s35
	v_lshl_add_u64 v[182:183], v[182:183], 0, s[14:15]
	s_mov_b32 m0, s40
	ds_read_b128 v[178:181], v188 offset:49152
	ds_read_b128 v[192:195], v188 offset:50176
	ds_read_b128 v[196:199], v188 offset:51200
	ds_read_b128 v[200:203], v188 offset:52224
	ds_read_b128 v[204:207], v188 offset:53248
	ds_read_b128 v[208:211], v188 offset:54272
	ds_read_b128 v[212:215], v188 offset:55296
	ds_read_b128 v[216:219], v188 offset:56320
	global_load_lds_dwordx4 v[182:183], off
	s_add_i32 m0, s40, 0x2000
	s_add_u32 s38, s38, 0x80080
	v_lshl_add_u64 v[182:183], v[220:221], 0, s[14:15]
	s_addc_u32 s39, s39, 0
	s_add_i32 s40, s58, s35
	global_load_lds_dwordx4 v[182:183], off
	v_lshl_add_u64 v[182:183], s[38:39], 0, v[148:149]
	s_mov_b32 m0, s40
	s_nop 0
	global_load_lds_dwordx4 v[182:183], off
	v_lshl_add_u64 v[182:183], s[38:39], 0, v[144:145]
	s_add_i32 m0, s40, 0x2000
	s_nop 0
	global_load_lds_dwordx4 v[182:183], off
	v_lshl_add_u64 v[182:183], v[222:223], 0, s[14:15]
	s_mov_b32 m0, s49
	s_nop 0
	global_load_lds_dwordx4 v[182:183], off
	v_lshl_add_u64 v[182:183], v[224:225], 0, s[14:15]
	s_mov_b32 m0, s50
	s_nop 0
	global_load_lds_dwordx4 v[182:183], off
	s_waitcnt vmcnt(8) lgkmcnt(0)
	s_setprio 1
	s_barrier
	v_mfma_f32_16x16x32_bf16 v[60:63], v[128:131], v[178:181], v[60:63]
	v_mfma_f32_16x16x32_bf16 v[56:59], v[136:139], v[178:181], v[56:59]
	v_mfma_f32_16x16x32_bf16 v[44:47], v[128:131], v[196:199], v[44:47]
	v_mfma_f32_16x16x32_bf16 v[40:43], v[136:139], v[196:199], v[40:43]
	v_mfma_f32_16x16x32_bf16 v[28:31], v[128:131], v[204:207], v[28:31]
	v_mfma_f32_16x16x32_bf16 v[24:27], v[136:139], v[204:207], v[24:27]
	v_mfma_f32_16x16x32_bf16 v[12:15], v[128:131], v[212:215], v[12:15]
	v_mfma_f32_16x16x32_bf16 v[8:11], v[136:139], v[212:215], v[8:11]
	v_mfma_f32_16x16x32_bf16 v[60:63], v[132:135], v[192:195], v[60:63]
	v_mfma_f32_16x16x32_bf16 v[56:59], v[140:143], v[192:195], v[56:59]
	v_mfma_f32_16x16x32_bf16 v[44:47], v[132:135], v[200:203], v[44:47]
	v_mfma_f32_16x16x32_bf16 v[40:43], v[140:143], v[200:203], v[40:43]
	v_mfma_f32_16x16x32_bf16 v[28:31], v[132:135], v[208:211], v[28:31]
	v_mfma_f32_16x16x32_bf16 v[24:27], v[140:143], v[208:211], v[24:27]
	v_mfma_f32_16x16x32_bf16 v[12:15], v[132:135], v[216:219], v[12:15]
	v_mfma_f32_16x16x32_bf16 v[8:11], v[140:143], v[216:219], v[8:11]
	s_setprio 0
	s_setprio 1
	v_mfma_f32_16x16x32_bf16 v[52:55], v[162:165], v[178:181], v[52:55]
	v_mfma_f32_16x16x32_bf16 v[48:51], v[170:173], v[178:181], v[48:51]
	v_mfma_f32_16x16x32_bf16 v[36:39], v[162:165], v[196:199], v[36:39]
	v_mfma_f32_16x16x32_bf16 v[32:35], v[170:173], v[196:199], v[32:35]
	s_add_i32 s56, s56, 2
	v_mfma_f32_16x16x32_bf16 v[20:23], v[162:165], v[204:207], v[20:23]
	s_add_u32 s6, s6, 0x100
	v_mfma_f32_16x16x32_bf16 v[16:19], v[170:173], v[204:207], v[16:19]
	s_addc_u32 s7, s7, 0
	v_mfma_f32_16x16x32_bf16 v[4:7], v[162:165], v[212:215], v[4:7]
	s_add_u32 s5, s5, 0x100
	v_mfma_f32_16x16x32_bf16 v[0:3], v[170:173], v[212:215], v[0:3]
	s_addc_u32 s25, s25, 0
	v_mfma_f32_16x16x32_bf16 v[52:55], v[166:169], v[192:195], v[52:55]
	s_cmp_gt_u32 s56, 29
	v_mfma_f32_16x16x32_bf16 v[48:51], v[174:177], v[192:195], v[48:51]
	v_mfma_f32_16x16x32_bf16 v[36:39], v[166:169], v[200:203], v[36:39]
	v_mfma_f32_16x16x32_bf16 v[32:35], v[174:177], v[200:203], v[32:35]
	v_mfma_f32_16x16x32_bf16 v[20:23], v[166:169], v[208:211], v[20:23]
	v_mfma_f32_16x16x32_bf16 v[16:19], v[174:177], v[208:211], v[16:19]
	v_mfma_f32_16x16x32_bf16 v[4:7], v[166:169], v[216:219], v[4:7]
	v_mfma_f32_16x16x32_bf16 v[0:3], v[174:177], v[216:219], v[0:3]
	s_cbranch_scc0 .Lrot_p4
	s_barrier
	s_setprio 0
	s_and_b64 vcc, exec, s[18:19]
	s_cbranch_vccz .LBB0_675
	s_barrier
